# also peeled first K iteration of the residual GEMM loop and replaced the per-step phase-table loads by scalar arithmetic
# speedup vs baseline: 1.0001x; 1.0000x over previous
; __global__ void __launch_bounds__(512, 2) mk_fwd(Args args) {
;     ...
;         const int op = PROG[step][0], L = PROG[step][1], F = PROG[step][2];
;         size_t zoff = 0; asm volatile("" : "+s"(zoff));
;         unsigned char* ws = args.ws + zoff;
;         float* xout = args.out + zoff;
;         bf16_t* XL = (bf16_t*)(ws + WS_XL);
;         bf16_t* XB = (bf16_t*)(ws + WS_H);
;         float* SS = (float*)(ws + WS_SS);
;         bf16_t* ACT = (bf16_t*)(ws + WS_ACT);
;         bf16_t* WIN = (bf16_t*)(ws + WS_WIN);
;         bf16_t* WOUT = (bf16_t*)(ws + WS_WOUT);
;         bf16_t* CIN = (bf16_t*)(ws + WS_CIN);
;         bf16_t* COUT = (bf16_t*)(ws + WS_COUT);
;         bf16_t* POOLW = (bf16_t*)(ws + WS_POOL);
;         bf16_t* WQKV = (bf16_t*)(ws + WS_WQKV);
;         bf16_t* WO = (bf16_t*)(ws + WS_WO);
;         bf16_t* CONV_U = ACT + (size_t)2 * M * D;
;         bf16_t* ATT_O = ACT + (size_t)M * NQKV;
.LBB0_14:
	s_mul_i32 s7, s18, 3
	s_getpc_b64 s[2:3]
	s_add_u32 s2, s2, _ZL4PROG@rel32@lo+4
	s_addc_u32 s3, s3, _ZL4PROG@rel32@hi+12
	s_mul_hi_i32 s6, s18, 3
	s_add_u32 s2, s2, s7
	s_addc_u32 s3, s3, s6
	v_mov_b32_e32 v192, v201
	s_mov_b64 s[8:9], 0
	s_getpc_b64 s[4:5]
	s_add_u32 s4, s4, _ZL4PROG@rel32@lo+6
	s_addc_u32 s5, s5, _ZL4PROG@rel32@hi+14
	s_add_u32 s4, s4, s7
	s_addc_u32 s5, s5, s6
	s_waitcnt lgkmcnt(0)
	s_add_u32 s70, s96, s8
	v_writelane_b32 v253, s8, 57
	s_addc_u32 s71, s97, s9
	s_mov_b32 s87, s18
	s_add_u32 s18, s70, 0x2a000000
	s_addc_u32 s19, s71, 0
	s_add_u32 s24, s70, 0xa000000
	s_addc_u32 s25, s71, 0
	s_add_u32 s82, s70, 0x9c00000
	s_addc_u32 s83, s71, 0
	v_writelane_b32 v253, s9, 58
	s_add_u32 s2, s70, 0x200000
	v_writelane_b32 v253, s2, 59
	s_addc_u32 s2, s71, 0
	v_writelane_b32 v253, s2, 60
	s_add_u32 s2, s70, 0x5a00000
	v_writelane_b32 v253, s2, 61
	s_addc_u32 s2, s71, 0
	v_writelane_b32 v253, s2, 62
	s_add_u32 s2, s70, 0x8600000
	v_writelane_b32 v253, s2, 63
	s_addc_u32 s2, s71, 0
	v_readfirstlane_b32 s90, v192
	v_writelane_b32 v254, s2, 0
	s_add_u32 s2, s70, 0x9200000
	v_writelane_b32 v254, s2, 1
	s_addc_u32 s2, s71, 0
	v_writelane_b32 v254, s2, 2
	s_add_u32 s2, s70, 0x9600000
	s_addc_u32 s3, s71, 0
	v_writelane_b32 v254, s2, 3
	s_lshr_b32 s6, s87, 3
	s_and_b32 s7, s87, 7
	s_lshl_b32 s7, s7, 2
	s_mov_b32 s4, 0x21543210
	s_cmp_eq_u32 s6, 1
	s_cselect_b32 s4, 0x21217621, s4
	s_cmp_eq_u32 s6, 2
	s_cselect_b32 s4, 0x32121a98, s4
	s_cmp_eq_u32 s6, 3
	s_cselect_b32 s4, 0x2154, s4
	s_lshr_b32 s4, s4, s7
	s_and_b32 s4, s4, 15
	s_cmp_ge_u32 s87, 8
	s_cselect_b32 s6, 1, 0
	s_cmp_ge_u32 s87, 14
	s_cselect_b32 s7, 1, 0
	s_add_u32 s6, s6, s7
	s_cmp_ge_u32 s87, 21
	s_cselect_b32 s7, 1, 0
	s_add_u32 s6, s6, s7
	s_lshl_b32 s6, s6, 8
	s_or_b32 s4, s4, s6
	v_writelane_b32 v254, s3, 4
	s_add_u32 s2, s70, 0x9700000
	s_addc_u32 s3, s71, 0
	v_writelane_b32 v254, s2, 5
	s_mov_b32 s5, 0xf9830c0
	s_bitcmp1_b32 s5, s87
	s_cselect_b32 s5, 1, 0
	v_writelane_b32 v254, s3, 6
	s_add_u32 s2, s70, 0x9a00000
	s_addc_u32 s3, s71, 0
	v_writelane_b32 v254, s2, 7
	s_and_b32 s69, s4, 0xff
	s_cmp_lt_i32 s69, 1
	v_writelane_b32 v254, s3, 8
	s_mov_b64 s[2:3], -1
	s_cbranch_scc1 .LBB0_461
	s_lshr_b32 s2, s4, 8
	s_and_b32 s91, s2, 0xff
	s_and_b32 s2, s5, 0xff
	s_add_u32 s58, s70, 0x12000000
	v_writelane_b32 v254, s2, 9
	s_addc_u32 s59, s71, 0
	s_and_b32 s65, 0xffff, s69
	v_writelane_b32 v254, s58, 10
	s_cmp_lg_u32 s65, 1
	s_mov_b64 s[2:3], -1
	v_writelane_b32 v254, s59, 11
	s_cbranch_scc0 .LBB0_443
	s_add_u32 s60, s70, 0x22000000
	s_addc_u32 s61, s71, 0
	v_writelane_b32 v254, s82, 12
	s_cmp_lt_i32 s69, 6
	s_nop 0
	v_writelane_b32 v254, s83, 13
	s_cbranch_scc1 .LBB0_21
	s_cmp_gt_i32 s65, 7
	s_cbranch_scc0 .LBB0_22
	s_cmp_gt_i32 s65, 8
	s_cbranch_scc0 .LBB0_23
	v_writelane_b32 v254, s86, 14
	v_writelane_b32 v254, s92, 15
	s_cmp_gt_i32 s65, 9
	s_nop 0
	v_writelane_b32 v254, s93, 16
	v_writelane_b32 v254, s94, 17
	v_writelane_b32 v254, s95, 18
	v_writelane_b32 v254, s87, 19
	v_writelane_b32 v254, s90, 20
	v_writelane_b32 v254, s91, 21
	v_writelane_b32 v254, s60, 22
	s_nop 1
	v_writelane_b32 v254, s61, 23
	v_writelane_b32 v254, s65, 24
	v_writelane_b32 v254, s69, 25
	s_cbranch_scc0 .LBB0_24
	s_cmp_eq_u32 s65, 10
	s_mov_b64 s[2:3], 0
	s_cselect_b64 s[4:5], -1, 0
	s_branch .LBB0_25

; #define PG8_STAGE(bufoff, gbase, voff) do { _Pragma("unroll") for (int _i = 0; _i < 2; ++_i) \
;         __builtin_amdgcn_global_load_lds((const unsigned*)((const char*)(gbase) + (voff)[_i]), (LAS unsigned*)(lds + (bufoff) + ldsw + _i * 8192), 16, 0, 0); } while (0)
; #define PG8_LDA(dst, b, h) do { _Pragma("unroll") for (int m = 0; m < 4; ++m) _Pragma("unroll") for (int k = 0; k < 2; ++k) dst[m][k] = *(const LAS bf16x8*)(lds + PG8_SA(b, h) + aoff + m * 2048 + k * 1024); } while (0)
; #define PG8_LDB(dst, b, h) do { _Pragma("unroll") for (int n = 0; n < 2; ++n) _Pragma("unroll") for (int k = 0; k < 2; ++k) dst[n][k] = *(const LAS bf16x8*)(lds + PG8_SB(b, h) + boff + n * 2048 + k * 1024); } while (0)
; #define PG8_MMA(ai, bj, At, Bt) do { __builtin_amdgcn_s_setprio(1); _Pragma("unroll") for (int m = 0; m < 4; ++m) _Pragma("unroll") for (int n = 0; n < 2; ++n) _Pragma("unroll") for (int k = 0; k < 2; ++k) \
;         acc[ai][bj][m][n] = __builtin_amdgcn_mfma_f32_16x16x32_bf16(Bt[n][k], At[m][k], acc[ai][bj][m][n], 0, 0, 0); __builtin_amdgcn_s_setprio(0); } while (0)
; #define PG8_WAIT_V(n) asm volatile("s_waitcnt vmcnt(" #n ")" ::: "memory")
; template <class Epi>
; __device__ __forceinline__ void gemm_phase(LAS unsigned char* lds, const Gemm g, const StaticOrder& S, const Epi& E, const int tid) {
;     ...
;             const char* a1 = cA + (size_t)(t + 1) * kstepA;
;             const char* a2 = last ? nA : cA + (size_t)(t + 2) * kstepA; const char* b2 = last ? nB : cB + (size_t)(t + 2) * kstep;
;             const char* a3 = a2 + kstepA; const char* b3 = b2 + kstep;
;             PG8_LDB(B0, 0, 0); PG8_LDB(B1, 0, 1); PG8_SCHED; PG8_LDA(At, 0, 0); PG8_STAGE(PG8_SA(1, 1), a1 + hstepA, voffA);
;             PG8_WAIT_V(8); PG8_WAIT_L(0); PG8_BAR; PG8_MMA(0, 0, At, B0); PG8_MMA(0, 1, At, B1); PG8_BAR; PG8_SCHED;
;             PG8_LDA(At, 0, 1); PG8_STAGE(PG8_SB(0, 0), b2, voffB); PG8_STAGE(PG8_SB(0, 1), b2 + hstepB, voffB); PG8_STAGE(PG8_SA(0, 0), a2, voffA);
;             PG8_WAIT_V(8); PG8_WAIT_L(0); PG8_BAR; PG8_MMA(1, 0, At, B0); PG8_MMA(1, 1, At, B1); PG8_BAR; PG8_SCHED;
;     ...
; #pragma unroll
;         for (int a = 0; a < 2; ++a)
; #pragma unroll
;             for (int b = 0; b < 2; ++b)
; #pragma unroll
;                 for (int m = 0; m < 4; ++m)
; #pragma unroll
;                     for (int n = 0; n < 2; ++n) acc[a][b][m][n] = (f32x4){0.f, 0.f, 0.f, 0.f};
.LBB0_392:
	s_add_u32 s71, s2, s21
	s_addc_u32 s72, s3, 0
	s_add_u32 s73, s28, 0x100
	s_addc_u32 s75, s29, 0
	s_mov_b64 s[28:29], 0
	s_waitcnt lgkmcnt(0)
	s_add_u32 s80, s28, 1
	s_addc_u32 s81, s29, 0
	s_add_u32 s34, s28, 2
	s_addc_u32 s35, s29, 0
	s_lshl_b64 s[52:53], s[34:35], s61
	s_add_u32 s29, s2, s52
	s_addc_u32 s52, s3, s53
	s_cmp_eq_u32 s65, s28
	s_cselect_b32 s53, s9, s52
	s_cselect_b32 s52, s8, s29
	s_cselect_b32 s82, s50, s73
	s_cselect_b32 s83, s51, s75
	s_add_u32 s28, s52, s40
	s_addc_u32 s29, s53, s41
	s_add_i32 s84, 0, 0x10000
	s_add_i32 s85, 0, 0x14000
	v_add_u32_e32 v140, s84, v225
	v_add_u32_e32 v156, s85, v225
	ds_read_b128 v[124:127], v140
	ds_read_b128 v[128:131], v140 offset:1024
	ds_read_b128 v[136:139], v140 offset:2048
	ds_read_b128 v[140:143], v140 offset:3072
	ds_read_b128 v[144:147], v156
	ds_read_b128 v[148:151], v156 offset:1024
	ds_read_b128 v[152:155], v156 offset:2048
	ds_read_b128 v[156:159], v156 offset:3072
	s_lshl_b64 s[80:81], s[80:81], s61
	s_add_u32 s80, s71, s80
	s_addc_u32 s81, s72, s81
	v_lshl_add_u64 v[178:179], s[80:81], 0, v[194:195]
	s_add_i32 m0, s23, 0xc000
	ds_read_b128 v[160:163], v226
	ds_read_b128 v[164:167], v226 offset:1024
	ds_read_b128 v[168:171], v226 offset:2048
	ds_read_b128 v[172:175], v226 offset:3072
	ds_read_b128 v[202:205], v226 offset:4096
	ds_read_b128 v[206:209], v226 offset:5120
	ds_read_b128 v[210:213], v226 offset:6144
	ds_read_b128 v[214:217], v226 offset:7168
	global_load_lds_dwordx4 v[178:179], off
	v_lshl_add_u64 v[178:179], s[80:81], 0, v[198:199]
	s_add_i32 m0, s23, 0xe000
	s_nop 0
	global_load_lds_dwordx4 v[178:179], off
	s_waitcnt vmcnt(8)
	s_waitcnt lgkmcnt(0)
	s_barrier
	v_mfma_f32_16x16x32_bf16 v[132:135], v[124:127], v[160:163], 0
	v_mfma_f32_16x16x32_bf16 v[120:123], v[136:139], v[160:163], 0
	v_mfma_f32_16x16x32_bf16 v[108:111], v[124:127], v[168:171], 0
	v_mfma_f32_16x16x32_bf16 v[104:107], v[136:139], v[168:171], 0
	v_mfma_f32_16x16x32_bf16 v[92:95], v[124:127], v[202:205], 0
	v_mfma_f32_16x16x32_bf16 v[88:91], v[136:139], v[202:205], 0
	v_mfma_f32_16x16x32_bf16 v[76:79], v[124:127], v[210:213], 0
	v_mfma_f32_16x16x32_bf16 v[72:75], v[136:139], v[210:213], 0
	v_mfma_f32_16x16x32_bf16 v[132:135], v[128:131], v[164:167], v[132:135]
	v_mfma_f32_16x16x32_bf16 v[120:123], v[140:143], v[164:167], v[120:123]
	v_mfma_f32_16x16x32_bf16 v[108:111], v[128:131], v[172:175], v[108:111]
	v_mfma_f32_16x16x32_bf16 v[104:107], v[140:143], v[172:175], v[104:107]
	v_mfma_f32_16x16x32_bf16 v[92:95], v[128:131], v[206:209], v[92:95]
	v_mfma_f32_16x16x32_bf16 v[88:91], v[140:143], v[206:209], v[88:91]
	v_mfma_f32_16x16x32_bf16 v[76:79], v[128:131], v[214:217], v[76:79]
	v_mfma_f32_16x16x32_bf16 v[72:75], v[140:143], v[214:217], v[72:75]
	v_mfma_f32_16x16x32_bf16 v[116:119], v[144:147], v[160:163], 0
	v_mfma_f32_16x16x32_bf16 v[112:115], v[152:155], v[160:163], 0
	v_mfma_f32_16x16x32_bf16 v[100:103], v[144:147], v[168:171], 0
	v_mfma_f32_16x16x32_bf16 v[96:99], v[152:155], v[168:171], 0
	v_mfma_f32_16x16x32_bf16 v[84:87], v[144:147], v[202:205], 0
	v_mfma_f32_16x16x32_bf16 v[80:83], v[152:155], v[202:205], 0
	v_mfma_f32_16x16x32_bf16 v[68:71], v[144:147], v[210:213], 0
	v_mfma_f32_16x16x32_bf16 v[64:67], v[152:155], v[210:213], 0
	v_mfma_f32_16x16x32_bf16 v[116:119], v[148:151], v[164:167], v[116:119]
	v_mfma_f32_16x16x32_bf16 v[112:115], v[156:159], v[164:167], v[112:115]
	v_mfma_f32_16x16x32_bf16 v[100:103], v[148:151], v[172:175], v[100:103]
	v_mfma_f32_16x16x32_bf16 v[96:99], v[156:159], v[172:175], v[96:99]
	v_mfma_f32_16x16x32_bf16 v[84:87], v[148:151], v[206:209], v[84:87]
	v_mfma_f32_16x16x32_bf16 v[80:83], v[156:159], v[206:209], v[80:83]
	v_mfma_f32_16x16x32_bf16 v[68:71], v[148:151], v[214:217], v[68:71]
	v_mfma_f32_16x16x32_bf16 v[64:67], v[156:159], v[214:217], v[64:67]
	s_barrier
	s_add_i32 s80, s84, s17
	v_lshl_add_u64 v[178:179], s[82:83], 0, v[176:177]
	s_mov_b32 m0, s80
	ds_read_b128 v[160:163], v226 offset:16384
	ds_read_b128 v[164:167], v226 offset:17408
	ds_read_b128 v[168:171], v226 offset:18432
	ds_read_b128 v[172:175], v226 offset:19456
	ds_read_b128 v[202:205], v226 offset:20480
	ds_read_b128 v[206:209], v226 offset:21504
	ds_read_b128 v[210:213], v226 offset:22528
	ds_read_b128 v[214:217], v226 offset:23552
	global_load_lds_dwordx4 v[178:179], off
	s_add_i32 m0, s80, 0x2000
	s_add_u32 s80, s82, s42
	v_lshl_add_u64 v[180:181], s[82:83], 0, v[196:197]
	s_addc_u32 s81, s83, s43
	s_add_i32 s82, s85, s17
	global_load_lds_dwordx4 v[180:181], off
	v_lshl_add_u64 v[218:219], s[80:81], 0, v[176:177]
	s_mov_b32 m0, s82
	v_lshl_add_u64 v[228:229], s[80:81], 0, v[196:197]
	global_load_lds_dwordx4 v[218:219], off
	s_add_i32 m0, s82, 0x2000
	v_lshl_add_u64 v[230:231], s[52:53], 0, v[194:195]
	global_load_lds_dwordx4 v[228:229], off
	s_mov_b32 m0, s23
	s_nop 0
	global_load_lds_dwordx4 v[230:231], off
	v_lshl_add_u64 v[230:231], s[52:53], 0, v[198:199]
	s_mov_b32 m0, s54
	s_nop 0
	global_load_lds_dwordx4 v[230:231], off
	s_waitcnt vmcnt(8)
	s_waitcnt lgkmcnt(0)
	s_barrier
; #define PG8_STAGE(bufoff, gbase, voff) do { _Pragma("unroll") for (int _i = 0; _i < 2; ++_i) \
;         __builtin_amdgcn_global_load_lds((const unsigned*)((const char*)(gbase) + (voff)[_i]), (LAS unsigned*)(lds + (bufoff) + ldsw + _i * 8192), 16, 0, 0); } while (0)
; #define PG8_LDA(dst, b, h) do { _Pragma("unroll") for (int m = 0; m < 4; ++m) _Pragma("unroll") for (int k = 0; k < 2; ++k) dst[m][k] = *(const LAS bf16x8*)(lds + PG8_SA(b, h) + aoff + m * 2048 + k * 1024); } while (0)
; #define PG8_LDB(dst, b, h) do { _Pragma("unroll") for (int n = 0; n < 2; ++n) _Pragma("unroll") for (int k = 0; k < 2; ++k) dst[n][k] = *(const LAS bf16x8*)(lds + PG8_SB(b, h) + boff + n * 2048 + k * 1024); } while (0)
; #define PG8_MMA(ai, bj, At, Bt) do { __builtin_amdgcn_s_setprio(1); _Pragma("unroll") for (int m = 0; m < 4; ++m) _Pragma("unroll") for (int n = 0; n < 2; ++n) _Pragma("unroll") for (int k = 0; k < 2; ++k) \
;         acc[ai][bj][m][n] = __builtin_amdgcn_mfma_f32_16x16x32_bf16(Bt[n][k], At[m][k], acc[ai][bj][m][n], 0, 0, 0); __builtin_amdgcn_s_setprio(0); } while (0)
; #define PG8_WAIT_V(n) asm volatile("s_waitcnt vmcnt(" #n ")" ::: "memory")
; #define PG8_WAIT_L(n) asm volatile("s_waitcnt lgkmcnt(" #n ")" ::: "memory")
; #define PG8_BAR __builtin_amdgcn_s_barrier()
; #define PG8_SCHED __builtin_amdgcn_sched_barrier(0)
; template <class Epi>
; __device__ __forceinline__ void gemm_phase(LAS unsigned char* lds, const Gemm g, const StaticOrder& S, const Epi& E, const int tid) {
;     ...
;             PG8_WAIT_V(8); PG8_WAIT_L(0); PG8_BAR; PG8_MMA(1, 0, At, B0); PG8_MMA(1, 1, At, B1); PG8_BAR; PG8_SCHED;
;             PG8_LDB(B0, 1, 0); PG8_LDB(B1, 1, 1); PG8_SCHED; PG8_LDA(At, 1, 0); PG8_STAGE(PG8_SA(0, 1), a2 + hstepA, voffA);
;             PG8_WAIT_V(8); PG8_WAIT_L(0); PG8_BAR; PG8_MMA(0, 0, At, B0); PG8_MMA(0, 1, At, B1); PG8_BAR; PG8_SCHED;
	v_mfma_f32_16x16x32_bf16 v[60:63], v[124:127], v[160:163], 0
	v_mfma_f32_16x16x32_bf16 v[56:59], v[136:139], v[160:163], 0
	v_mfma_f32_16x16x32_bf16 v[44:47], v[124:127], v[168:171], 0
	v_mfma_f32_16x16x32_bf16 v[40:43], v[136:139], v[168:171], 0
	v_mfma_f32_16x16x32_bf16 v[28:31], v[124:127], v[202:205], 0
	v_mfma_f32_16x16x32_bf16 v[24:27], v[136:139], v[202:205], 0
	v_mfma_f32_16x16x32_bf16 v[12:15], v[124:127], v[210:213], 0
	v_mfma_f32_16x16x32_bf16 v[8:11], v[136:139], v[210:213], 0
	v_mfma_f32_16x16x32_bf16 v[60:63], v[128:131], v[164:167], v[60:63]
	v_mfma_f32_16x16x32_bf16 v[56:59], v[140:143], v[164:167], v[56:59]
	v_mfma_f32_16x16x32_bf16 v[44:47], v[128:131], v[172:175], v[44:47]
	v_mfma_f32_16x16x32_bf16 v[40:43], v[140:143], v[172:175], v[40:43]
	v_mfma_f32_16x16x32_bf16 v[28:31], v[128:131], v[206:209], v[28:31]
	v_mfma_f32_16x16x32_bf16 v[24:27], v[140:143], v[206:209], v[24:27]
	v_mfma_f32_16x16x32_bf16 v[12:15], v[128:131], v[214:217], v[12:15]
	v_mfma_f32_16x16x32_bf16 v[8:11], v[140:143], v[214:217], v[8:11]
	v_mfma_f32_16x16x32_bf16 v[52:55], v[144:147], v[160:163], 0
	v_mfma_f32_16x16x32_bf16 v[48:51], v[152:155], v[160:163], 0
	v_mfma_f32_16x16x32_bf16 v[36:39], v[144:147], v[168:171], 0
	v_mfma_f32_16x16x32_bf16 v[32:35], v[152:155], v[168:171], 0
	v_mfma_f32_16x16x32_bf16 v[20:23], v[144:147], v[202:205], 0
	v_mfma_f32_16x16x32_bf16 v[16:19], v[152:155], v[202:205], 0
	v_mfma_f32_16x16x32_bf16 v[4:7], v[144:147], v[210:213], 0
	v_mfma_f32_16x16x32_bf16 v[0:3], v[152:155], v[210:213], 0
	v_mfma_f32_16x16x32_bf16 v[52:55], v[148:151], v[164:167], v[52:55]
	v_mfma_f32_16x16x32_bf16 v[48:51], v[156:159], v[164:167], v[48:51]
	v_mfma_f32_16x16x32_bf16 v[36:39], v[148:151], v[172:175], v[36:39]
	v_mfma_f32_16x16x32_bf16 v[32:35], v[156:159], v[172:175], v[32:35]
	v_mfma_f32_16x16x32_bf16 v[20:23], v[148:151], v[206:209], v[20:23]
	v_mfma_f32_16x16x32_bf16 v[16:19], v[156:159], v[206:209], v[16:19]
	v_mfma_f32_16x16x32_bf16 v[4:7], v[148:151], v[214:217], v[4:7]
	v_mfma_f32_16x16x32_bf16 v[0:3], v[156:159], v[214:217], v[0:3]
	s_barrier
	s_add_i32 s80, 0, 0x18000
	s_add_i32 s81, 0, 0x1c000
	v_add_u32_e32 v140, s80, v225
	v_add_u32_e32 v156, s81, v225
	ds_read_b128 v[124:127], v140
	ds_read_b128 v[128:131], v140 offset:1024
	ds_read_b128 v[136:139], v140 offset:2048
	ds_read_b128 v[140:143], v140 offset:3072
	ds_read_b128 v[144:147], v156
	ds_read_b128 v[148:151], v156 offset:1024
	ds_read_b128 v[152:155], v156 offset:2048
	ds_read_b128 v[156:159], v156 offset:3072
	s_add_u32 s52, s52, s21
	s_addc_u32 s53, s53, 0
	s_mov_b32 m0, s55
	v_lshl_add_u64 v[230:231], s[52:53], 0, v[194:195]
	ds_read_b128 v[160:163], v226 offset:32768
	ds_read_b128 v[164:167], v226 offset:33792
	ds_read_b128 v[168:171], v226 offset:34816
	ds_read_b128 v[172:175], v226 offset:35840
	ds_read_b128 v[202:205], v226 offset:36864
	ds_read_b128 v[206:209], v226 offset:37888
	ds_read_b128 v[210:213], v226 offset:38912
	ds_read_b128 v[214:217], v226 offset:39936
	global_load_lds_dwordx4 v[230:231], off
	v_lshl_add_u64 v[230:231], s[52:53], 0, v[198:199]
	s_mov_b32 m0, s56
	s_nop 0
	global_load_lds_dwordx4 v[230:231], off
	s_waitcnt vmcnt(8)
	s_waitcnt lgkmcnt(0)
	s_barrier
	v_mfma_f32_16x16x32_bf16 v[132:135], v[124:127], v[160:163], v[132:135]
	v_mfma_f32_16x16x32_bf16 v[120:123], v[136:139], v[160:163], v[120:123]
	v_mfma_f32_16x16x32_bf16 v[108:111], v[124:127], v[168:171], v[108:111]
	v_mfma_f32_16x16x32_bf16 v[104:107], v[136:139], v[168:171], v[104:107]
	v_mfma_f32_16x16x32_bf16 v[92:95], v[124:127], v[202:205], v[92:95]
	v_mfma_f32_16x16x32_bf16 v[88:91], v[136:139], v[202:205], v[88:91]
	v_mfma_f32_16x16x32_bf16 v[76:79], v[124:127], v[210:213], v[76:79]
	v_mfma_f32_16x16x32_bf16 v[72:75], v[136:139], v[210:213], v[72:75]
	v_mfma_f32_16x16x32_bf16 v[132:135], v[128:131], v[164:167], v[132:135]
	v_mfma_f32_16x16x32_bf16 v[120:123], v[140:143], v[164:167], v[120:123]
	v_mfma_f32_16x16x32_bf16 v[108:111], v[128:131], v[172:175], v[108:111]
	v_mfma_f32_16x16x32_bf16 v[104:107], v[140:143], v[172:175], v[104:107]
	v_mfma_f32_16x16x32_bf16 v[92:95], v[128:131], v[206:209], v[92:95]
	v_mfma_f32_16x16x32_bf16 v[88:91], v[140:143], v[206:209], v[88:91]
	v_mfma_f32_16x16x32_bf16 v[76:79], v[128:131], v[214:217], v[76:79]
	v_mfma_f32_16x16x32_bf16 v[72:75], v[140:143], v[214:217], v[72:75]
	v_mfma_f32_16x16x32_bf16 v[116:119], v[144:147], v[160:163], v[116:119]
	v_mfma_f32_16x16x32_bf16 v[112:115], v[152:155], v[160:163], v[112:115]
	v_mfma_f32_16x16x32_bf16 v[100:103], v[144:147], v[168:171], v[100:103]
	v_mfma_f32_16x16x32_bf16 v[96:99], v[152:155], v[168:171], v[96:99]
	v_mfma_f32_16x16x32_bf16 v[84:87], v[144:147], v[202:205], v[84:87]
	v_mfma_f32_16x16x32_bf16 v[80:83], v[152:155], v[202:205], v[80:83]
	v_mfma_f32_16x16x32_bf16 v[68:71], v[144:147], v[210:213], v[68:71]
	v_mfma_f32_16x16x32_bf16 v[64:67], v[152:155], v[210:213], v[64:67]
	v_mfma_f32_16x16x32_bf16 v[116:119], v[148:151], v[164:167], v[116:119]
	v_mfma_f32_16x16x32_bf16 v[112:115], v[156:159], v[164:167], v[112:115]
	v_mfma_f32_16x16x32_bf16 v[100:103], v[148:151], v[172:175], v[100:103]
	v_mfma_f32_16x16x32_bf16 v[96:99], v[156:159], v[172:175], v[96:99]
	v_mfma_f32_16x16x32_bf16 v[84:87], v[148:151], v[206:209], v[84:87]
	v_mfma_f32_16x16x32_bf16 v[80:83], v[156:159], v[206:209], v[80:83]
	v_mfma_f32_16x16x32_bf16 v[68:71], v[148:151], v[214:217], v[68:71]
	v_mfma_f32_16x16x32_bf16 v[64:67], v[156:159], v[214:217], v[64:67]
	s_barrier
; #define PG8_STAGE(bufoff, gbase, voff) do { _Pragma("unroll") for (int _i = 0; _i < 2; ++_i) \
;         __builtin_amdgcn_global_load_lds((const unsigned*)((const char*)(gbase) + (voff)[_i]), (LAS unsigned*)(lds + (bufoff) + ldsw + _i * 8192), 16, 0, 0); } while (0)
; #define PG8_LDA(dst, b, h) do { _Pragma("unroll") for (int m = 0; m < 4; ++m) _Pragma("unroll") for (int k = 0; k < 2; ++k) dst[m][k] = *(const LAS bf16x8*)(lds + PG8_SA(b, h) + aoff + m * 2048 + k * 1024); } while (0)
; #define PG8_MMA(ai, bj, At, Bt) do { __builtin_amdgcn_s_setprio(1); _Pragma("unroll") for (int m = 0; m < 4; ++m) _Pragma("unroll") for (int n = 0; n < 2; ++n) _Pragma("unroll") for (int k = 0; k < 2; ++k) \
;         acc[ai][bj][m][n] = __builtin_amdgcn_mfma_f32_16x16x32_bf16(Bt[n][k], At[m][k], acc[ai][bj][m][n], 0, 0, 0); __builtin_amdgcn_s_setprio(0); } while (0)
; #define PG8_WAIT_V(n) asm volatile("s_waitcnt vmcnt(" #n ")" ::: "memory")
; #define PG8_WAIT_L(n) asm volatile("s_waitcnt lgkmcnt(" #n ")" ::: "memory")
; #define PG8_BAR __builtin_amdgcn_s_barrier()
; #define PG8_SCHED __builtin_amdgcn_sched_barrier(0)
; template <class Epi>
; __device__ __forceinline__ void gemm_phase(LAS unsigned char* lds, const Gemm g, const StaticOrder& S, const Epi& E, const int tid) {
;     ...
;             PG8_LDA(At, 1, 1); PG8_STAGE(PG8_SB(1, 0), b3, voffB); PG8_STAGE(PG8_SB(1, 1), b3 + hstepB, voffB); PG8_STAGE(PG8_SA(1, 0), a3, voffA);
;             PG8_WAIT_V(8); PG8_WAIT_L(0); PG8_BAR; PG8_MMA(1, 0, At, B0); PG8_MMA(1, 1, At, B1); PG8_BAR; PG8_SCHED;
;         }
	s_add_i32 s52, s80, s17
	v_lshl_add_u64 v[178:179], v[178:179], 0, s[36:37]
	s_mov_b32 m0, s52
	ds_read_b128 v[160:163], v226 offset:49152
	ds_read_b128 v[164:167], v226 offset:50176
	ds_read_b128 v[168:171], v226 offset:51200
	ds_read_b128 v[172:175], v226 offset:52224
	ds_read_b128 v[202:205], v226 offset:53248
	ds_read_b128 v[206:209], v226 offset:54272
	ds_read_b128 v[210:213], v226 offset:55296
	ds_read_b128 v[214:217], v226 offset:56320
	global_load_lds_dwordx4 v[178:179], off
	v_lshl_add_u64 v[178:179], v[180:181], 0, s[36:37]
	s_add_i32 m0, s52, 0x2000
	s_add_i32 s52, s81, s17
	global_load_lds_dwordx4 v[178:179], off
	v_lshl_add_u64 v[178:179], v[218:219], 0, s[36:37]
	s_mov_b32 m0, s52
	s_nop 0
	global_load_lds_dwordx4 v[178:179], off
	v_lshl_add_u64 v[178:179], v[228:229], 0, s[36:37]
	s_add_i32 m0, s52, 0x2000
	s_nop 0
	global_load_lds_dwordx4 v[178:179], off
	v_lshl_add_u64 v[178:179], s[28:29], 0, v[194:195]
	s_mov_b32 m0, s59
	s_nop 0
	global_load_lds_dwordx4 v[178:179], off
	v_lshl_add_u64 v[178:179], s[28:29], 0, v[198:199]
	s_mov_b32 m0, s60
	s_nop 0
	global_load_lds_dwordx4 v[178:179], off
	s_waitcnt vmcnt(8)
	s_waitcnt lgkmcnt(0)
	s_barrier
	v_mfma_f32_16x16x32_bf16 v[60:63], v[124:127], v[160:163], v[60:63]
	v_mfma_f32_16x16x32_bf16 v[56:59], v[136:139], v[160:163], v[56:59]
	v_mfma_f32_16x16x32_bf16 v[44:47], v[124:127], v[168:171], v[44:47]
	v_mfma_f32_16x16x32_bf16 v[40:43], v[136:139], v[168:171], v[40:43]
	v_mfma_f32_16x16x32_bf16 v[28:31], v[124:127], v[202:205], v[28:31]
	v_mfma_f32_16x16x32_bf16 v[24:27], v[136:139], v[202:205], v[24:27]
	v_mfma_f32_16x16x32_bf16 v[12:15], v[124:127], v[210:213], v[12:15]
	v_mfma_f32_16x16x32_bf16 v[8:11], v[136:139], v[210:213], v[8:11]
	v_mfma_f32_16x16x32_bf16 v[60:63], v[128:131], v[164:167], v[60:63]
	v_mfma_f32_16x16x32_bf16 v[56:59], v[140:143], v[164:167], v[56:59]
	v_mfma_f32_16x16x32_bf16 v[44:47], v[128:131], v[172:175], v[44:47]
	v_mfma_f32_16x16x32_bf16 v[40:43], v[140:143], v[172:175], v[40:43]
	v_mfma_f32_16x16x32_bf16 v[28:31], v[128:131], v[206:209], v[28:31]
	v_mfma_f32_16x16x32_bf16 v[24:27], v[140:143], v[206:209], v[24:27]
	v_mfma_f32_16x16x32_bf16 v[12:15], v[128:131], v[214:217], v[12:15]
	v_mfma_f32_16x16x32_bf16 v[8:11], v[140:143], v[214:217], v[8:11]
	v_mfma_f32_16x16x32_bf16 v[52:55], v[144:147], v[160:163], v[52:55]
	v_mfma_f32_16x16x32_bf16 v[48:51], v[152:155], v[160:163], v[48:51]
	v_mfma_f32_16x16x32_bf16 v[36:39], v[144:147], v[168:171], v[36:39]
	v_mfma_f32_16x16x32_bf16 v[32:35], v[152:155], v[168:171], v[32:35]
	v_mfma_f32_16x16x32_bf16 v[20:23], v[144:147], v[202:205], v[20:23]
	v_mfma_f32_16x16x32_bf16 v[16:19], v[152:155], v[202:205], v[16:19]
	v_mfma_f32_16x16x32_bf16 v[4:7], v[144:147], v[210:213], v[4:7]
	v_mfma_f32_16x16x32_bf16 v[0:3], v[152:155], v[210:213], v[0:3]
	v_mfma_f32_16x16x32_bf16 v[52:55], v[148:151], v[164:167], v[52:55]
	v_mfma_f32_16x16x32_bf16 v[48:51], v[156:159], v[164:167], v[48:51]
	v_mfma_f32_16x16x32_bf16 v[36:39], v[148:151], v[172:175], v[36:39]
	v_mfma_f32_16x16x32_bf16 v[32:35], v[156:159], v[172:175], v[32:35]
	v_mfma_f32_16x16x32_bf16 v[20:23], v[148:151], v[206:209], v[20:23]
	v_mfma_f32_16x16x32_bf16 v[16:19], v[156:159], v[206:209], v[16:19]
	v_mfma_f32_16x16x32_bf16 v[4:7], v[148:151], v[214:217], v[4:7]
	v_mfma_f32_16x16x32_bf16 v[0:3], v[156:159], v[214:217], v[0:3]
	s_barrier
	s_add_u32 s73, s73, 0x100
	s_addc_u32 s75, s75, 0
	s_mov_b64 s[28:29], s[34:35]
